# kind-0 in-proj phases: M-tiles interleaved across XCDs (tm=(xl&7)*8+xg) so prefix/latent row tiles are balanced per XCD
# speedup vs baseline: 1.0104x; 1.0078x over previous
.LBB0_283:
	s_or_b64 exec, exec, s[6:7]
	v_readlane_b32 s2, v253, 0
	v_readlane_b32 s3, v253, 1
	s_waitcnt lgkmcnt(0)
	s_barrier
	s_load_dwordx2 s[0:1], s[2:3], 0x168
	s_lshr_b32 s97, s69, 3
	v_bfe_u32 v233, v146, 4, 2
	v_bfe_u32 v230, v146, 6, 1
	v_bfe_u32 v236, v146, 3, 3
	s_waitcnt lgkmcnt(0)
	s_lshr_b32 s96, s0, 3
	s_cmpk_lt_u32 s69, 0x500
	s_cselect_b64 s[0:1], -1, 0
	v_writelane_b32 v253, s0, 14
	s_cmpk_gt_u32 s69, 0x4ff
	v_lshrrev_b32_e32 v231, 7, v146
	v_lshlrev_b32_e32 v232, 7, v148
	v_lshlrev_b32_e32 v234, 6, v230
	v_lshlrev_b32_e32 v154, 2, v233
	v_lshlrev_b32_e32 v160, 3, v233
	v_and_b32_e32 v153, 3, v146
	v_bitop3_b32 v235, v233, v146, 7 bitop3:0x78
	v_or_b32_e32 v237, 8, v236
	v_or_b32_e32 v238, 16, v236
	v_or_b32_e32 v239, 24, v236
	v_or_b32_e32 v240, 32, v236
	v_or_b32_e32 v241, 40, v236
	v_or_b32_e32 v242, 48, v236
	v_or_b32_e32 v243, 56, v236
	v_lshlrev_b32_e32 v162, 5, v233
	v_writelane_b32 v253, s1, 15
	s_cbranch_scc1 .LBB0_302
	v_readlane_b32 s0, v253, 0
	v_readlane_b32 s1, v253, 1
	s_load_dwordx4 s[8:11], s[0:1], 0x158
	v_xor_b32_e32 v0, v149, v146
	v_lshlrev_b32_e32 v0, 4, v0
	v_mov_b32_e32 v129, 0
	v_and_b32_e32 v0, 0x70, v0
	s_waitcnt lgkmcnt(0)
	s_add_u32 s12, s10, 0x7200000
	s_addc_u32 s13, s11, 0
	s_add_u32 s14, s10, 0x2000000
	v_lshl_or_b32 v2, v231, 13, v232
	v_lshl_or_b32 v3, v230, 13, v232
	v_mov_b32_e32 v161, v129
	v_lshlrev_b32_e32 v6, 4, v235
	s_addc_u32 s15, s11, 0
	s_lshl_b32 s0, s69, 3
	v_lshl_or_b32 v159, v149, 7, v0
	v_lshl_add_u64 v[0:1], s[10:11], 0, v[160:161]
	v_or_b32_e32 v161, v2, v6
	v_or_b32_e32 v165, v3, v6
	v_bitop3_b32 v6, v233, v151, 4 bitop3:0x36
	s_and_b32 s3, s0, 56
	s_mov_b64 s[0:1], 0x3000000
	v_lshlrev_b32_e32 v6, 4, v6
	v_lshl_add_u64 v[130:131], v[0:1], 0, s[0:1]
	v_mul_u32_u24_e32 v1, 0x2400, v147
	v_and_b32_e32 v4, 48, v155
	v_and_b32_e32 v0, 0x70, v144
	v_or_b32_e32 v166, v2, v6
	v_lshlrev_b32_e32 v2, 1, v153
	v_or_b32_e32 v5, v1, v0
	v_or3_b32 v1, v1, v4, v2
	s_movk_i32 s0, 0x240
	v_mov_b32_e32 v163, v129
	v_or_b32_e32 v167, v3, v6
	v_mad_u32_u24 v168, v233, s0, v1
	v_lshl_add_u64 v[2:3], s[10:11], 0, v[162:163]
	s_mov_b64 s[0:1], 0xf67c000
	v_and_b32_e32 v128, 0x380, v146
	v_lshl_add_u64 v[132:133], v[2:3], 0, s[0:1]
	v_lshl_add_u64 v[2:3], s[10:11], 0, v[128:129]
	v_mov_b32_e32 v1, v129
	s_and_b32 s16, s97, 7
	s_cmp_gt_u32 s16, 3
	v_mul_u32_u24_e32 v4, 0x90, v236
	v_lshl_add_u64 v[0:1], v[2:3], 0, v[0:1]
	s_mov_b64 s[0:1], 0xb440000
	v_lshlrev_b32_e32 v158, 4, v151
	v_lshlrev_b32_e32 v164, 6, v231
	s_cselect_b64 s[16:17], -1, 0
	v_lshl_add_u64 v[134:135], v[0:1], 0, s[0:1]
	s_mov_b64 s[10:11], 0x10000
	s_mov_b32 s4, 0x10000
	s_mov_b64 s[18:19], 0x20000
	s_mov_b32 s5, 0x20000
	s_mov_b64 s[20:21], 0x30000
	s_mov_b32 s26, 0x30000
	s_mov_b32 s23, 0
	s_movk_i32 s27, 0xf80
	s_movk_i32 s28, 0x1780
	s_movk_i32 s29, 0x1f80
	v_add_u32_e32 v163, v5, v4
	s_mov_b32 s30, 0x1fff000
	v_lshlrev_b32_e32 v136, 2, v154
	s_movk_i32 s31, 0x4000
	v_mov_b32_e32 v169, 0x800
	v_mov_b32_e32 v170, 0x1000
	v_mov_b32_e32 v171, 0x1800
	v_mov_b32_e32 v172, 0x14000
	s_mov_b32 s33, s97
	s_branch .LBB0_286

.LBB0_286:
	s_and_b32 s0, s33, 7
	s_lshl_b32 s0, s0, 3
	s_lshr_b32 s1, s3, 3
	s_or_b32 s0, s0, s1
	s_lshl_b32 s34, s0, 7
	v_or_b32_e32 v0, s34, v149
	v_lshl_or_b32 v128, v0, 11, v158
	v_lshl_add_u64 v[98:99], s[14:15], 0, v[128:129]
	v_add_co_u32_e32 v6, vcc, 0x10000, v98
	s_lshl_b32 s1, s33, 4
	s_nop 0
	v_addc_co_u32_e32 v7, vcc, 0, v99, vcc
	s_and_b32 s0, s1, 0x7fffff80
	v_add_co_u32_e32 v8, vcc, 0x20000, v98
	v_or_b32_e32 v0, s0, v149
	s_nop 0
	v_addc_co_u32_e32 v9, vcc, 0, v99, vcc
	v_lshl_or_b32 v96, v0, 11, v158
	v_add_co_u32_e32 v10, vcc, 0x30000, v98
	v_mov_b32_e32 v97, v129
	s_nop 0
	v_addc_co_u32_e32 v11, vcc, 0, v99, vcc
	v_lshl_add_u64 v[100:101], s[12:13], 0, v[96:97]
	v_add_co_u32_e32 v12, vcc, s4, v100
	v_addc_co_u32_e32 v13, vcc, 0, v101, vcc
	v_add_co_u32_e32 v46, vcc, s5, v100
	v_addc_co_u32_e32 v47, vcc, 0, v101, vcc
	v_add_co_u32_e32 v48, vcc, s26, v100
	v_addc_co_u32_e32 v49, vcc, 0, v101, vcc
	s_movk_i32 s1, 0x100
	s_mov_b32 s6, s23
	v_mov_b32_e32 v0, 0
	v_mov_b32_e32 v1, v129
	v_mov_b32_e32 v2, v129
	v_mov_b32_e32 v3, v129
	v_mov_b32_e32 v4, 0
	v_mov_b32_e32 v5, v129
	v_mov_b32_e32 v6, v129
	v_mov_b32_e32 v7, v129
	v_mov_b32_e32 v8, 0
	v_mov_b32_e32 v9, v129
	v_mov_b32_e32 v10, v129
	v_mov_b32_e32 v11, v129
	v_mov_b32_e32 v12, 0
	v_mov_b32_e32 v13, v129
	v_lshl_add_u64 v[102:103], v[100:101], 0, s[10:11]
	v_lshl_add_u64 v[104:105], v[100:101], 0, s[18:19]
	v_lshl_add_u64 v[106:107], v[100:101], 0, s[20:21]
	v_lshl_add_u64 v[108:109], v[98:99], 0, s[10:11]
	v_lshl_add_u64 v[110:111], v[98:99], 0, s[18:19]
	v_lshl_add_u64 v[112:113], v[98:99], 0, s[20:21]
	s_barrier
	v_mov_b32_e32 v46, v129
	v_mov_b32_e32 v47, v129
	v_mov_b32_e32 v48, 0
	v_mov_b32_e32 v49, v129
	v_mov_b32_e32 v50, v129
	v_mov_b32_e32 v51, v129
	v_mov_b32_e32 v52, 0
	v_mov_b32_e32 v53, v129
	v_mov_b32_e32 v54, v129
	v_mov_b32_e32 v55, v129
	v_mov_b32_e32 v56, 0
	v_mov_b32_e32 v57, v129
	v_mov_b32_e32 v58, v129
	v_mov_b32_e32 v59, v129
	v_mov_b32_e32 v60, 0
	v_mov_b32_e32 v61, v129
	v_mov_b32_e32 v62, v129
	v_mov_b32_e32 v63, v129
	v_mov_b32_e32 v14, v129
	v_mov_b32_e32 v15, v129
	v_mov_b32_e32 v16, 0
	v_mov_b32_e32 v17, v129
	v_mov_b32_e32 v18, v129
	v_mov_b32_e32 v19, v129
	v_mov_b32_e32 v20, 0
	v_mov_b32_e32 v21, v129
	v_mov_b32_e32 v22, v129
	v_mov_b32_e32 v23, v129
	v_mov_b32_e32 v24, 0
	v_mov_b32_e32 v25, v129
	v_mov_b32_e32 v26, v129
	v_mov_b32_e32 v27, v129
	v_mov_b32_e32 v28, 0
	v_mov_b32_e32 v29, v129
	v_mov_b32_e32 v30, v129
	v_mov_b32_e32 v31, v129
	v_mov_b32_e32 v32, 0
	v_mov_b32_e32 v33, v129
	v_mov_b32_e32 v34, v129
	v_mov_b32_e32 v35, v129
	v_mov_b32_e32 v36, 0
	v_mov_b32_e32 v37, v129
	v_mov_b32_e32 v38, v129
	v_mov_b32_e32 v39, v129
	v_mov_b32_e32 v40, 0
	v_mov_b32_e32 v41, v129
	v_mov_b32_e32 v42, v129
	v_mov_b32_e32 v43, v129
	v_mov_b32_e32 v44, 0
	v_mov_b32_e32 v45, v129
	v_readlane_b32 s100, v253, 0
	v_readlane_b32 s101, v253, 1
	s_load_dwordx2 s[100:101], s[100:101], 0x160
	v_lshrrev_b32_e32 v71, 6, v146
	s_nop 0
	v_readfirstlane_b32 s24, v71
	v_lshrrev_b32_e32 v69, 3, v146
	v_and_b32_e32 v70, 7, v146
	v_xor_b32_e32 v70, v69, v70
	v_and_b32_e32 v70, 7, v70
	v_lshlrev_b32_e32 v70, 4, v70
	v_lshl_or_b32 v68, v69, 11, v70
	v_add_u32_e32 v69, 0x10000, v68
	v_add_u32_e32 v70, 0x20000, v68
	v_add_u32_e32 v71, 0x30000, v68
	s_and_b32 s98, s33, 7
	s_lshl_b32 s98, s98, 3
	s_and_b32 s99, s69, 7
	s_or_b32 s98, s98, s99
	s_lshl_b32 s98, s98, 18
	s_add_u32 s98, s98, 0x2000000
	s_lshr_b32 s99, s33, 3
	s_lshl_b32 s99, s99, 18
	s_add_u32 s99, s99, 0x7200000
	s_lshl_b32 s24, s24, 10
	s_waitcnt lgkmcnt(0)
	s_mov_b32 m0, s99
	s_add_u32 s98, s100, s98
	s_addc_u32 s99, s101, 0
	s_add_u32 s100, s100, m0
	s_addc_u32 s101, s101, 0
	s_add_u32 m0, s24, 0x0
	s_nop 0
	global_load_lds_dwordx4 v68, s[98:99]
	s_add_u32 m0, s24, 0x1000
	s_nop 0
	global_load_lds_dwordx4 v69, s[98:99]
	s_add_u32 m0, s24, 0x2000
	s_nop 0
	global_load_lds_dwordx4 v70, s[98:99]
	s_add_u32 m0, s24, 0x3000
	s_nop 0
	global_load_lds_dwordx4 v71, s[98:99]
	s_add_u32 m0, s24, 0x8000
	s_nop 0
	global_load_lds_dwordx4 v68, s[100:101]
	s_add_u32 m0, s24, 0x9000
	s_nop 0
	global_load_lds_dwordx4 v69, s[100:101]
	s_add_u32 m0, s24, 0xa000
	s_nop 0
	global_load_lds_dwordx4 v70, s[100:101]
	s_add_u32 m0, s24, 0xb000
	s_nop 0
	global_load_lds_dwordx4 v71, s[100:101]
	s_add_u32 s98, s98, 0x80
	s_addc_u32 s99, s99, 0
	s_add_u32 s100, s100, 0x80
	s_addc_u32 s101, s101, 0
	s_waitcnt vmcnt(0)
	s_waitcnt lgkmcnt(0)
	s_barrier

.LBB0_524:
	s_or_b64 exec, exec, s[6:7]
	s_cmpk_lt_u32 s69, 0x800
	s_cselect_b64 s[20:21], -1, 0
	s_cmpk_gt_u32 s69, 0x7ff
	s_waitcnt lgkmcnt(0)
	s_barrier
	s_cbranch_scc1 .LBB0_547
	v_readlane_b32 s0, v253, 0
	v_readlane_b32 s1, v253, 1
	s_load_dwordx4 s[12:15], s[0:1], 0x158
	v_xor_b32_e32 v0, v149, v146
	v_lshlrev_b32_e32 v0, 4, v0
	v_lshl_or_b32 v2, v231, 13, v232
	v_lshl_or_b32 v3, v230, 13, v232
	s_waitcnt lgkmcnt(0)
	s_add_u32 s16, s14, 0x7700000
	s_addc_u32 s17, s15, 0
	s_add_u32 s22, s14, 0xdc40000
	v_lshlrev_b32_e32 v6, 4, v235
	s_addc_u32 s23, s15, 0
	s_lshl_b32 s0, s69, 3
	v_and_b32_e32 v0, 0x70, v0
	v_mov_b32_e32 v161, 0
	v_or_b32_e32 v174, v2, v6
	v_or_b32_e32 v175, v3, v6
	v_bitop3_b32 v6, v233, v151, 4 bitop3:0x36
	s_and_b32 s3, s0, 56
	v_lshl_or_b32 v172, v149, 7, v0
	v_lshl_add_u64 v[0:1], s[14:15], 0, v[160:161]
	s_mov_b64 s[0:1], 0x3000000
	v_lshlrev_b32_e32 v6, 4, v6
	s_and_b32 s24, s97, 7
	s_cmp_lt_u32 s24, 4
	v_lshl_add_u64 v[128:129], v[0:1], 0, s[0:1]
	v_mul_u32_u24_e32 v1, 0x2400, v147
	v_and_b32_e32 v4, 48, v155
	v_and_b32_e32 v0, 0x70, v144
	v_or_b32_e32 v176, v2, v6
	v_lshlrev_b32_e32 v2, 1, v153
	s_cselect_b64 s[24:25], -1, 0
	s_and_b32 s26, s97, 7
	s_cmp_gt_u32 s26, 3
	v_or_b32_e32 v5, v1, v0
	v_or3_b32 v1, v1, v4, v2
	s_movk_i32 s0, 0x240
	v_mov_b32_e32 v163, v161
	s_cselect_b64 s[26:27], -1, 0
	v_or_b32_e32 v177, v3, v6
	v_mad_u32_u24 v178, v233, s0, v1
	s_add_u32 s4, s14, 0xfaa2100
	v_lshl_add_u64 v[2:3], s[14:15], 0, v[162:163]
	s_mov_b64 s[0:1], 0xf67c000
	v_and_b32_e32 v160, 0x380, v146
	s_addc_u32 s5, s15, 0
	v_lshl_add_u64 v[130:131], v[2:3], 0, s[0:1]
	v_lshl_add_u64 v[2:3], s[14:15], 0, v[160:161]
	v_mov_b32_e32 v1, v161
	v_mul_u32_u24_e32 v4, 0x90, v236
	s_add_u32 s28, s14, 0xfa8a100
	v_lshl_add_u64 v[0:1], v[2:3], 0, v[0:1]
	s_mov_b64 s[0:1], 0xb440000
	v_lshlrev_b32_e32 v159, 4, v151
	v_lshlrev_b32_e32 v173, 6, v231
	s_addc_u32 s29, s15, 0
	v_lshl_add_u64 v[132:133], v[0:1], 0, s[0:1]
	s_mov_b64 s[14:15], 0x10000
	s_mov_b32 s38, 0x10000
	s_mov_b64 s[30:31], 0x20000
	s_mov_b32 s39, 0x20000
	s_mov_b64 s[34:35], 0x30000
	s_mov_b32 s40, 0x30000
	s_mov_b32 s37, 0
	v_lshlrev_b32_e32 v134, 2, v154
	v_mov_b32_e32 v179, 0x358637bd
	s_mov_b32 s41, 0x800000
	v_add_u32_e32 v180, v5, v4
	s_mov_b32 s42, 0x27ff000
	s_mov_b32 s43, s97
	s_branch .LBB0_527

.LBB0_527:
	s_and_b32 s0, s43, 7
	s_lshl_b32 s0, s0, 3
	s_lshr_b32 s1, s3, 3
	s_or_b32 s0, s0, s1
	s_lshl_b32 s44, s0, 7
	v_or_b32_e32 v0, s44, v149
	v_lshl_or_b32 v160, v0, 11, v159
	v_lshl_add_u64 v[30:31], s[22:23], 0, v[160:161]
	v_add_co_u32_e32 v4, vcc, 0x10000, v30
	s_lshl_b32 s1, s43, 4
	s_nop 0
	v_addc_co_u32_e32 v5, vcc, 0, v31, vcc
	s_and_b32 s0, s1, 0x7fffff80
	v_add_co_u32_e32 v12, vcc, 0x20000, v30
	v_or_b32_e32 v0, s0, v149
	s_nop 0
	v_addc_co_u32_e32 v13, vcc, 0, v31, vcc
	v_lshl_or_b32 v24, v0, 11, v159
	v_add_co_u32_e32 v16, vcc, 0x30000, v30
	v_mov_b32_e32 v25, v161
	s_nop 0
	v_addc_co_u32_e32 v17, vcc, 0, v31, vcc
	v_lshl_add_u64 v[52:53], s[16:17], 0, v[24:25]
	v_add_co_u32_e32 v18, vcc, s38, v52
	s_nop 0
	v_addc_co_u32_e32 v19, vcc, 0, v53, vcc
	v_add_co_u32_e32 v28, vcc, s39, v52
	s_nop 0
	v_addc_co_u32_e32 v29, vcc, 0, v53, vcc
	v_add_co_u32_e32 v58, vcc, s40, v52
	s_nop 0
	v_addc_co_u32_e32 v59, vcc, 0, v53, vcc
	s_nop 0
	s_nop 0
	s_nop 0
	s_movk_i32 s1, 0x100
	s_mov_b32 s6, s37
	v_mov_b32_e32 v8, 0
	v_mov_b32_e32 v9, v161
	v_mov_b32_e32 v10, v161
	v_mov_b32_e32 v11, v161
	v_mov_b32_e32 v26, 0
	v_mov_b32_e32 v27, v161
	v_mov_b32_e32 v28, v161
	v_mov_b32_e32 v29, v161
	v_mov_b32_e32 v16, 0
	v_mov_b32_e32 v17, v161
	v_mov_b32_e32 v18, v161
	v_mov_b32_e32 v19, v161
	v_mov_b32_e32 v60, 0
	v_mov_b32_e32 v61, v161
	v_lshl_add_u64 v[58:59], v[52:53], 0, s[14:15]
	v_lshl_add_u64 v[104:105], v[52:53], 0, s[30:31]
	v_lshl_add_u64 v[106:107], v[52:53], 0, s[34:35]
	v_lshl_add_u64 v[108:109], v[30:31], 0, s[14:15]
	v_lshl_add_u64 v[110:111], v[30:31], 0, s[30:31]
	v_lshl_add_u64 v[112:113], v[30:31], 0, s[34:35]
	s_barrier
	v_mov_b32_e32 v88, 0
	v_mov_b32_e32 v89, v161
	v_mov_b32_e32 v90, v161
	v_mov_b32_e32 v91, v161
	v_mov_b32_e32 v76, 0
	v_mov_b32_e32 v77, v161
	v_mov_b32_e32 v78, v161
	v_mov_b32_e32 v79, v161
	v_mov_b32_e32 v80, 0
	v_mov_b32_e32 v81, v161
	v_mov_b32_e32 v82, v161
	v_mov_b32_e32 v83, v161
	v_mov_b32_e32 v84, 0
	v_mov_b32_e32 v85, v161
	v_mov_b32_e32 v86, v161
	v_mov_b32_e32 v87, v161
	v_mov_b32_e32 v74, v161
	v_mov_b32_e32 v75, v161
	v_mov_b32_e32 v62, v161
	v_mov_b32_e32 v63, v161
	v_mov_b32_e32 v36, 0
	v_mov_b32_e32 v37, v161
	v_mov_b32_e32 v38, v161
	v_mov_b32_e32 v39, v161
	v_mov_b32_e32 v54, 0
	v_mov_b32_e32 v55, v161
	v_mov_b32_e32 v56, v161
	v_mov_b32_e32 v57, v161
	v_mov_b32_e32 v32, 0
	v_mov_b32_e32 v33, v161
	v_mov_b32_e32 v34, v161
	v_mov_b32_e32 v35, v161
	v_mov_b32_e32 v64, 0
	v_mov_b32_e32 v65, v161
	v_mov_b32_e32 v66, v161
	v_mov_b32_e32 v67, v161
	v_mov_b32_e32 v40, 0
	v_mov_b32_e32 v41, v161
	v_mov_b32_e32 v42, v161
	v_mov_b32_e32 v43, v161
	v_mov_b32_e32 v48, 0
	v_mov_b32_e32 v49, v161
	v_mov_b32_e32 v50, v161
	v_mov_b32_e32 v51, v161
	v_mov_b32_e32 v68, 0
	v_mov_b32_e32 v69, v161
	v_mov_b32_e32 v70, v161
	v_mov_b32_e32 v71, v161
	v_mov_b32_e32 v72, 0
	v_mov_b32_e32 v73, v161
	v_readlane_b32 s100, v253, 0
	v_readlane_b32 s101, v253, 1
	s_load_dwordx2 s[100:101], s[100:101], 0x160
	v_lshrrev_b32_e32 v7, 6, v146
	s_nop 0
	v_readfirstlane_b32 s8, v7
	v_lshrrev_b32_e32 v5, 3, v146
	v_and_b32_e32 v6, 7, v146
	v_xor_b32_e32 v6, v5, v6
	v_and_b32_e32 v6, 7, v6
	v_lshlrev_b32_e32 v6, 4, v6
	v_lshl_or_b32 v4, v5, 11, v6
	v_add_u32_e32 v5, 0x10000, v4
	v_add_u32_e32 v6, 0x20000, v4
	v_add_u32_e32 v7, 0x30000, v4
	s_and_b32 s98, s43, 7
	s_lshl_b32 s98, s98, 3
	s_and_b32 s99, s69, 7
	s_or_b32 s98, s98, s99
	s_lshl_b32 s98, s98, 18
	s_add_u32 s98, s98, 0xdc40000
	s_lshr_b32 s99, s43, 3
	s_lshl_b32 s99, s99, 18
	s_add_u32 s99, s99, 0x7700000
	s_lshl_b32 s8, s8, 10
	s_waitcnt lgkmcnt(0)
	s_mov_b32 m0, s99
	s_add_u32 s98, s100, s98
	s_addc_u32 s99, s101, 0
	s_add_u32 s100, s100, m0
	s_addc_u32 s101, s101, 0
	s_add_u32 m0, s8, 0x0
	s_nop 0
	global_load_lds_dwordx4 v4, s[98:99]
	s_add_u32 m0, s8, 0x1000
	s_nop 0
	global_load_lds_dwordx4 v5, s[98:99]
	s_add_u32 m0, s8, 0x2000
	s_nop 0
	global_load_lds_dwordx4 v6, s[98:99]
	s_add_u32 m0, s8, 0x3000
	s_nop 0
	global_load_lds_dwordx4 v7, s[98:99]
	s_add_u32 m0, s8, 0x8000
	s_nop 0
	global_load_lds_dwordx4 v4, s[100:101]
	s_add_u32 m0, s8, 0x9000
	s_nop 0
	global_load_lds_dwordx4 v5, s[100:101]
	s_add_u32 m0, s8, 0xa000
	s_nop 0
	global_load_lds_dwordx4 v6, s[100:101]
	s_add_u32 m0, s8, 0xb000
	s_nop 0
	global_load_lds_dwordx4 v7, s[100:101]
	s_add_u32 s98, s98, 0x80
	s_addc_u32 s99, s99, 0
	s_add_u32 s100, s100, 0x80
	s_addc_u32 s101, s101, 0
	s_waitcnt vmcnt(0)
	s_waitcnt lgkmcnt(0)
	s_barrier

.LBB0_1162:
	s_or_b64 exec, exec, s[10:11]
	v_readlane_b32 s0, v253, 14
	v_readlane_b32 s1, v253, 15
	s_andn2_b64 vcc, exec, s[0:1]
	v_and_b32_e32 v128, 56, v152
	s_waitcnt lgkmcnt(0)
	s_barrier
	s_cbranch_vccnz .LBB0_1185
	v_readlane_b32 s0, v253, 0
	v_readlane_b32 s1, v253, 1
	s_load_dwordx4 s[16:19], s[0:1], 0x158
	v_bitop3_b32 v7, v220, v146, 7 bitop3:0x78
	v_lshl_or_b32 v1, v231, 13, v232
	v_lshl_or_b32 v4, v230, 13, v232
	v_lshlrev_b32_e32 v7, 4, v7
	s_waitcnt lgkmcnt(0)
	s_add_u32 s20, s18, 0x8740000
	s_addc_u32 s21, s19, 0
	s_add_u32 s22, s18, 0xdc40000
	s_addc_u32 s23, s19, 0
	s_lshl_b32 s0, s69, 3
	v_mov_b32_e32 v131, 0
	v_lshlrev_b32_e32 v130, 3, v220
	v_and_b32_e32 v5, 48, v155
	v_or_b32_e32 v155, v1, v7
	v_or_b32_e32 v171, v4, v7
	v_bitop3_b32 v7, v220, v151, 4 bitop3:0x36
	s_and_b32 s3, s0, 56
	v_lshl_add_u64 v[2:3], s[18:19], 0, v[130:131]
	s_mov_b64 s[0:1], 0x3000000
	v_lshlrev_b32_e32 v7, 4, v7
	s_and_b32 s24, s97, 7
	s_cmp_lt_u32 s24, 4
	v_lshl_add_u64 v[132:133], v[2:3], 0, s[0:1]
	v_mul_u32_u24_e32 v3, 0x2400, v147
	v_or_b32_e32 v172, v1, v7
	v_lshlrev_b32_e32 v1, 1, v153
	v_xor_b32_e32 v0, v149, v146
	s_cselect_b64 s[24:25], -1, 0
	s_and_b32 s26, s97, 7
	s_cmp_gt_u32 s26, 3
	v_or3_b32 v1, v3, v5, v1
	s_movk_i32 s0, 0x240
	v_lshlrev_b32_e32 v130, 5, v220
	v_lshlrev_b32_e32 v0, 4, v0
	s_cselect_b64 s[26:27], -1, 0
	v_lshlrev_b32_e32 v2, 1, v128
	v_or_b32_e32 v173, v4, v7
	v_mad_u32_u24 v174, v220, s0, v1
	s_add_u32 s4, s18, 0xfaa2100
	v_lshl_add_u64 v[4:5], s[18:19], 0, v[130:131]
	s_mov_b64 s[0:1], 0xf67c000
	v_and_b32_e32 v130, 0x380, v146
	v_and_b32_e32 v0, 0x70, v0
	v_or_b32_e32 v6, v3, v2
	v_lshrrev_b32_e32 v175, 3, v156
	s_addc_u32 s5, s19, 0
	v_lshl_add_u64 v[134:135], v[4:5], 0, s[0:1]
	v_lshl_add_u64 v[4:5], s[18:19], 0, v[130:131]
	v_mov_b32_e32 v3, v131
	v_lshl_or_b32 v159, v149, 7, v0
	v_lshlrev_b32_e32 v0, 2, v220
	v_mul_u32_u24_e32 v1, 0x90, v175
	s_add_u32 s28, s18, 0xfa9a100
	v_lshl_add_u64 v[2:3], v[4:5], 0, v[2:3]
	s_mov_b64 s[0:1], 0xb440000
	v_lshlrev_b32_e32 v129, 4, v151
	v_lshlrev_b32_e32 v170, 6, v231
	v_or_b32_e32 v176, 8, v175
	v_or_b32_e32 v177, 16, v175
	v_or_b32_e32 v178, 24, v175
	v_or_b32_e32 v179, 32, v175
	v_or_b32_e32 v180, 40, v175
	v_or_b32_e32 v181, 48, v175
	v_or_b32_e32 v182, 56, v175
	s_addc_u32 s29, s19, 0
	v_lshl_add_u64 v[136:137], v[2:3], 0, s[0:1]
	s_mov_b64 s[18:19], 0x10000
	s_mov_b32 s8, 0x10000
	s_mov_b64 s[30:31], 0x20000
	s_mov_b32 s9, 0x20000
	s_mov_b64 s[34:35], 0x30000
	s_mov_b32 s38, 0x30000
	s_mov_b32 s37, 0
	v_lshlrev_b32_e32 v138, 2, v0
	v_mov_b32_e32 v183, 0x358637bd
	s_mov_b32 s39, 0x800000
	s_movk_i32 s40, 0x1400
	s_movk_i32 s41, 0x1780
	s_movk_i32 s42, 0x1f80
	v_add_u32_e32 v184, v6, v1
	s_mov_b32 s43, 0x57ff000
	s_movk_i32 s44, 0x4000
	v_mov_b32_e32 v185, 0x1000
	v_mov_b32_e32 v186, 0x1800
	v_mov_b32_e32 v187, 0x14000
	s_mov_b32 s45, s97
	s_branch .LBB0_1165

.LBB0_1165:
	s_and_b32 s0, s45, 7
	s_lshl_b32 s0, s0, 3
	s_lshr_b32 s1, s3, 3
	s_or_b32 s0, s0, s1
	s_lshl_b32 s46, s0, 7
	v_or_b32_e32 v0, s46, v149
	v_lshl_or_b32 v130, v0, 11, v129
	v_lshl_add_u64 v[30:31], s[22:23], 0, v[130:131]
	v_add_co_u32_e32 v4, vcc, 0x10000, v30
	s_lshl_b32 s1, s45, 4
	s_nop 0
	v_addc_co_u32_e32 v5, vcc, 0, v31, vcc
	s_and_b32 s0, s1, 0x7fffff80
	v_add_co_u32_e32 v12, vcc, 0x20000, v30
	v_or_b32_e32 v0, s0, v149
	s_nop 0
	v_addc_co_u32_e32 v13, vcc, 0, v31, vcc
	v_lshl_or_b32 v24, v0, 11, v129
	v_add_co_u32_e32 v16, vcc, 0x30000, v30
	v_mov_b32_e32 v25, v131
	s_nop 0
	v_addc_co_u32_e32 v17, vcc, 0, v31, vcc
	v_lshl_add_u64 v[52:53], s[20:21], 0, v[24:25]
	v_add_co_u32_e32 v18, vcc, s8, v52
	s_nop 0
	v_addc_co_u32_e32 v19, vcc, 0, v53, vcc
	v_add_co_u32_e32 v28, vcc, s9, v52
	s_nop 0
	v_addc_co_u32_e32 v29, vcc, 0, v53, vcc
	v_add_co_u32_e32 v58, vcc, s38, v52
	s_nop 0
	v_addc_co_u32_e32 v59, vcc, 0, v53, vcc
	s_nop 0
	s_nop 0
	s_nop 0
	s_movk_i32 s1, 0x100
	s_mov_b32 s6, s37
	v_mov_b32_e32 v8, 0
	v_mov_b32_e32 v9, v131
	v_mov_b32_e32 v10, v131
	v_mov_b32_e32 v11, v131
	v_mov_b32_e32 v26, 0
	v_mov_b32_e32 v27, v131
	v_mov_b32_e32 v28, v131
	v_mov_b32_e32 v29, v131
	v_mov_b32_e32 v16, 0
	v_mov_b32_e32 v17, v131
	v_mov_b32_e32 v18, v131
	v_mov_b32_e32 v19, v131
	v_mov_b32_e32 v60, 0
	v_mov_b32_e32 v61, v131
	v_lshl_add_u64 v[58:59], v[52:53], 0, s[18:19]
	v_lshl_add_u64 v[104:105], v[52:53], 0, s[30:31]
	v_lshl_add_u64 v[106:107], v[52:53], 0, s[34:35]
	v_lshl_add_u64 v[108:109], v[30:31], 0, s[18:19]
	v_lshl_add_u64 v[110:111], v[30:31], 0, s[30:31]
	v_lshl_add_u64 v[112:113], v[30:31], 0, s[34:35]
	s_barrier
	v_mov_b32_e32 v88, 0
	v_mov_b32_e32 v89, v131
	v_mov_b32_e32 v90, v131
	v_mov_b32_e32 v91, v131
	v_mov_b32_e32 v76, 0
	v_mov_b32_e32 v77, v131
	v_mov_b32_e32 v78, v131
	v_mov_b32_e32 v79, v131
	v_mov_b32_e32 v80, 0
	v_mov_b32_e32 v81, v131
	v_mov_b32_e32 v82, v131
	v_mov_b32_e32 v83, v131
	v_mov_b32_e32 v84, 0
	v_mov_b32_e32 v85, v131
	v_mov_b32_e32 v86, v131
	v_mov_b32_e32 v87, v131
	v_mov_b32_e32 v74, v131
	v_mov_b32_e32 v75, v131
	v_mov_b32_e32 v62, v131
	v_mov_b32_e32 v63, v131
	v_mov_b32_e32 v36, 0
	v_mov_b32_e32 v37, v131
	v_mov_b32_e32 v38, v131
	v_mov_b32_e32 v39, v131
	v_mov_b32_e32 v54, 0
	v_mov_b32_e32 v55, v131
	v_mov_b32_e32 v56, v131
	v_mov_b32_e32 v57, v131
	v_mov_b32_e32 v32, 0
	v_mov_b32_e32 v33, v131
	v_mov_b32_e32 v34, v131
	v_mov_b32_e32 v35, v131
	v_mov_b32_e32 v64, 0
	v_mov_b32_e32 v65, v131
	v_mov_b32_e32 v66, v131
	v_mov_b32_e32 v67, v131
	v_mov_b32_e32 v40, 0
	v_mov_b32_e32 v41, v131
	v_mov_b32_e32 v42, v131
	v_mov_b32_e32 v43, v131
	v_mov_b32_e32 v48, 0
	v_mov_b32_e32 v49, v131
	v_mov_b32_e32 v50, v131
	v_mov_b32_e32 v51, v131
	v_mov_b32_e32 v68, 0
	v_mov_b32_e32 v69, v131
	v_mov_b32_e32 v70, v131
	v_mov_b32_e32 v71, v131
	v_mov_b32_e32 v72, 0
	v_mov_b32_e32 v73, v131
	v_readlane_b32 s100, v253, 0
	v_readlane_b32 s101, v253, 1
	s_load_dwordx2 s[100:101], s[100:101], 0x160
	v_lshrrev_b32_e32 v7, 6, v146
	s_nop 0
	v_readfirstlane_b32 s10, v7
	v_lshrrev_b32_e32 v5, 3, v146
	v_and_b32_e32 v6, 7, v146
	v_xor_b32_e32 v6, v5, v6
	v_and_b32_e32 v6, 7, v6
	v_lshlrev_b32_e32 v6, 4, v6
	v_lshl_or_b32 v4, v5, 11, v6
	v_add_u32_e32 v5, 0x10000, v4
	v_add_u32_e32 v6, 0x20000, v4
	v_add_u32_e32 v7, 0x30000, v4
	s_and_b32 s98, s45, 7
	s_lshl_b32 s98, s98, 3
	s_and_b32 s99, s69, 7
	s_or_b32 s98, s98, s99
	s_lshl_b32 s98, s98, 18
	s_add_u32 s98, s98, 0xdc40000
	s_lshr_b32 s99, s45, 3
	s_lshl_b32 s99, s99, 18
	s_add_u32 s99, s99, 0x8740000
	s_lshl_b32 s10, s10, 10
	s_waitcnt lgkmcnt(0)
	s_mov_b32 m0, s99
	s_add_u32 s98, s100, s98
	s_addc_u32 s99, s101, 0
	s_add_u32 s100, s100, m0
	s_addc_u32 s101, s101, 0
	s_add_u32 m0, s10, 0x0
	s_nop 0
	global_load_lds_dwordx4 v4, s[98:99]
	s_add_u32 m0, s10, 0x1000
	s_nop 0
	global_load_lds_dwordx4 v5, s[98:99]
	s_add_u32 m0, s10, 0x2000
	s_nop 0
	global_load_lds_dwordx4 v6, s[98:99]
	s_add_u32 m0, s10, 0x3000
	s_nop 0
	global_load_lds_dwordx4 v7, s[98:99]
	s_add_u32 m0, s10, 0x8000
	s_nop 0
	global_load_lds_dwordx4 v4, s[100:101]
	s_add_u32 m0, s10, 0x9000
	s_nop 0
	global_load_lds_dwordx4 v5, s[100:101]
	s_add_u32 m0, s10, 0xa000
	s_nop 0
	global_load_lds_dwordx4 v6, s[100:101]
	s_add_u32 m0, s10, 0xb000
	s_nop 0
	global_load_lds_dwordx4 v7, s[100:101]
	s_add_u32 s98, s98, 0x80
	s_addc_u32 s99, s99, 0
	s_add_u32 s100, s100, 0x80
	s_addc_u32 s101, s101, 0
	s_waitcnt vmcnt(0)
	s_waitcnt lgkmcnt(0)
	s_barrier
